# loop-edge edit: wave-uniform mask tests in the cmp/slc/win tile loops use one s_and_b64 with exec instead of a 0/1 VGPR round trip
# speedup vs baseline: 1.0080x; 1.0080x over previous
; #define LAS __attribute__((address_space(3)))
; DI int crow(int reg, int hi) { return (reg & 3) + 8 * (reg >> 2) + 4 * hi; }
; #define MFMA32(a, b, c) __builtin_amdgcn_mfma_f32_32x32x16_bf16((a), (b), (c), 0, 0, 0)
; template <bool CMP> DI void tile_compute(LAS unsigned char* lds, int buf, const bf16x8 (&q)[4], int lo, int hv, ASt& st, f32x16& imp0, f32x16& imp1, int jt, LAS float* wsf, int lane) {
;     const int r = lane & 31, hi = lane >> 5;
;     const LAS unsigned char* kb0 = lds + A_KT + buf * 8192 + hi * 1024;
;     f32x16 p0 = {}, p1 = {};
; #pragma unroll
;     for (int s = 0; s < 4; ++s) { const LAS unsigned char* kb = kb0 + ((r ^ (4 * s + 2 * hi)) * 16);
;         const bf16x8 a0 = *(const LAS bf16x8*)(kb + s * 2048), a1 = *(const LAS bf16x8*)(kb + s * 2048 + 512);
;         p0 = MFMA32(a0, q[s], p0); p1 = MFMA32(a1, q[s], p1); }
;     const bool dead = lo > hv;
;     const bool part = !dead && (lo > 0 || hv < 63);
;     const bool anyPart = __builtin_amdgcn_ballot_w64(part) != 0ull;
;     if (anyPart) {
; #pragma unroll
;         for (int rg = 0; rg < 16; ++rg) { const int k0 = crow(rg, hi), k1 = k0 + 32;
;             p0[rg] = (k0 >= lo && k0 <= hv) ? p0[rg] : NEGB; p1[rg] = (k1 >= lo && k1 <= hv) ? p1[rg] : NEGB; }
;     }
; DI void nsa_unit(const Ctx& c0, int b, int g, int i, LAS unsigned char* lds) {
;     ...
;             int hv = jmax - 64 * k; hv = hv > 63 ? 63 : hv; const int lo = hv < 0 ? 64 : 0;
.LBB0_549:
	v_add_u32_e32 v242, s90, v137
	v_add_u32_e32 v72, v242, v139
	ds_read_b128 v[68:71], v72
	ds_read_b128 v[72:75], v72 offset:512
	v_add_u32_e32 v141, v242, v143
	ds_read_b128 v[234:237], v141 offset:2048
	ds_read_b128 v[238:241], v141 offset:2560
	v_add_u32_e32 v141, v242, v146
	s_waitcnt lgkmcnt(0)
	v_mfma_f32_32x32x16_bf16 v[84:99], v[68:71], v[112:115], 0
	v_cmp_gt_i32_e64 s[82:83], 63, v231
	v_mfma_f32_32x32x16_bf16 v[68:83], v[72:75], v[112:115], 0
	v_mfma_f32_32x32x16_bf16 v[84:99], v[234:237], v[100:103], v[84:99]
	v_mfma_f32_32x32x16_bf16 v[68:83], v[238:241], v[100:103], v[68:83]
	ds_read_b128 v[234:237], v141 offset:4096
	ds_read_b128 v[238:241], v141 offset:4608
	v_min_i32_e32 v141, 63, v231
	s_waitcnt lgkmcnt(0)
	v_mfma_f32_32x32x16_bf16 v[84:99], v[234:237], v[108:111], v[84:99]
	v_add_u32_e32 v235, v242, v147
	ds_read_b128 v[242:245], v235 offset:6144
	v_lshrrev_b32_e32 v234, 25, v231
	v_and_b32_e32 v234, 64, v234
	v_cmp_le_i32_e32 vcc, v234, v141
	v_cmp_gt_i32_e64 s[78:79], v234, v141
	v_mfma_f32_32x32x16_bf16 v[68:83], v[238:241], v[108:111], v[68:83]
	ds_read_b128 v[236:239], v235 offset:6656
	v_and_b32_e32 v235, 0x80000000, v231
	v_cmp_ne_u32_e64 s[80:81], 0, v235
	s_or_b64 s[12:13], s[82:83], s[80:81]
	s_and_b64 s[12:13], s[12:13], vcc
	s_and_b64 vcc, s[12:13], exec
	s_waitcnt lgkmcnt(0)
	v_mfma_f32_32x32x16_bf16 v[84:99], v[242:245], v[104:107], v[84:99]
	s_cmp_eq_u64 vcc, 0
	s_cselect_b64 s[12:13], -1, 0
	v_mfma_f32_32x32x16_bf16 v[68:83], v[236:239], v[104:107], v[68:83]
	s_cbranch_vccz .LBB0_551
	v_sub_u32_e32 v249, v141, v148
	v_sub_u32_e32 v249, v249, v234
	v_cmp_gt_i32_e32 vcc, 0, v249
	v_cmp_gt_i32_e64 s[80:81], 32, v249
	s_nop 7
	v_cndmask_b32_e32 v84, v84, v222, vcc
	v_cmp_gt_i32_e32 vcc, 1, v249
	v_cndmask_b32_e64 v68, v68, v222, s[80:81]
	v_cmp_gt_i32_e64 s[80:81], 33, v249
	v_cndmask_b32_e32 v85, v85, v222, vcc
	v_cmp_gt_i32_e32 vcc, 2, v249
	v_cndmask_b32_e64 v69, v69, v222, s[80:81]
	v_cmp_gt_i32_e64 s[80:81], 34, v249
	v_cndmask_b32_e32 v86, v86, v222, vcc
	v_cmp_gt_i32_e32 vcc, 3, v249
	v_cndmask_b32_e64 v70, v70, v222, s[80:81]
	v_cmp_gt_i32_e64 s[80:81], 35, v249
	v_cndmask_b32_e32 v87, v87, v222, vcc
	v_cmp_gt_i32_e32 vcc, 8, v249
	v_cndmask_b32_e64 v71, v71, v222, s[80:81]
	v_cmp_gt_i32_e64 s[80:81], 40, v249
	v_cndmask_b32_e32 v88, v88, v222, vcc
	v_cmp_gt_i32_e32 vcc, 9, v249
	v_cndmask_b32_e64 v72, v72, v222, s[80:81]
	v_cmp_gt_i32_e64 s[80:81], 41, v249
	v_cndmask_b32_e32 v89, v89, v222, vcc
	v_cmp_gt_i32_e32 vcc, 10, v249
	v_cndmask_b32_e64 v73, v73, v222, s[80:81]
	v_cmp_gt_i32_e64 s[80:81], 42, v249
	v_cndmask_b32_e32 v90, v90, v222, vcc
	v_cmp_gt_i32_e32 vcc, 11, v249
	v_cndmask_b32_e64 v74, v74, v222, s[80:81]
	v_cmp_gt_i32_e64 s[80:81], 43, v249
	v_cndmask_b32_e32 v91, v91, v222, vcc
	v_cmp_gt_i32_e32 vcc, 16, v249
	v_cndmask_b32_e64 v75, v75, v222, s[80:81]
	v_cmp_gt_i32_e64 s[80:81], 48, v249
	v_cndmask_b32_e32 v92, v92, v222, vcc
	v_cmp_gt_i32_e32 vcc, 17, v249
	v_cndmask_b32_e64 v76, v76, v222, s[80:81]
	v_cmp_gt_i32_e64 s[80:81], 49, v249
	v_cndmask_b32_e32 v93, v93, v222, vcc
	v_cmp_gt_i32_e32 vcc, 18, v249
	v_cndmask_b32_e64 v77, v77, v222, s[80:81]
	v_cmp_gt_i32_e64 s[80:81], 50, v249
	v_cndmask_b32_e32 v94, v94, v222, vcc
	v_cmp_gt_i32_e32 vcc, 19, v249
	v_cndmask_b32_e64 v78, v78, v222, s[80:81]
	v_cmp_gt_i32_e64 s[80:81], 51, v249
	v_cndmask_b32_e32 v95, v95, v222, vcc
	v_cmp_gt_i32_e32 vcc, 24, v249
	v_cndmask_b32_e64 v79, v79, v222, s[80:81]
	v_cmp_gt_i32_e64 s[80:81], 56, v249
	v_cndmask_b32_e32 v96, v96, v222, vcc
	v_cmp_gt_i32_e32 vcc, 25, v249
	v_cndmask_b32_e64 v80, v80, v222, s[80:81]
	v_cmp_gt_i32_e64 s[80:81], 57, v249
	v_cndmask_b32_e32 v97, v97, v222, vcc
	v_cmp_gt_i32_e32 vcc, 26, v249
	v_cndmask_b32_e64 v81, v81, v222, s[80:81]
	v_cmp_gt_i32_e64 s[80:81], 58, v249
	v_cndmask_b32_e32 v98, v98, v222, vcc
	v_cmp_gt_i32_e32 vcc, 27, v249
	v_cndmask_b32_e64 v82, v82, v222, s[80:81]
	v_cmp_gt_i32_e64 s[80:81], 59, v249
	v_cndmask_b32_e32 v99, v99, v222, vcc
	s_nop 0
	v_cndmask_b32_e64 v83, v83, v222, s[80:81]

; #define LAS __attribute__((address_space(3)))
; DI int crow(int reg, int hi) { return (reg & 3) + 8 * (reg >> 2) + 4 * hi; }
; #define MFMA32(a, b, c) __builtin_amdgcn_mfma_f32_32x32x16_bf16((a), (b), (c), 0, 0, 0)
; template <bool CMP> DI void tile_compute(LAS unsigned char* lds, int buf, const bf16x8 (&q)[4], int lo, int hv, ASt& st, f32x16& imp0, f32x16& imp1, int jt, LAS float* wsf, int lane) {
;     const int r = lane & 31, hi = lane >> 5;
;     const LAS unsigned char* kb0 = lds + A_KT + buf * 8192 + hi * 1024;
;     f32x16 p0 = {}, p1 = {};
; #pragma unroll
;     for (int s = 0; s < 4; ++s) { const LAS unsigned char* kb = kb0 + ((r ^ (4 * s + 2 * hi)) * 16);
;         const bf16x8 a0 = *(const LAS bf16x8*)(kb + s * 2048), a1 = *(const LAS bf16x8*)(kb + s * 2048 + 512);
;         p0 = MFMA32(a0, q[s], p0); p1 = MFMA32(a1, q[s], p1); }
;     const bool dead = lo > hv;
;     const bool part = !dead && (lo > 0 || hv < 63);
;     const bool anyPart = __builtin_amdgcn_ballot_w64(part) != 0ull;
;     if (anyPart) {
; #pragma unroll
;         for (int rg = 0; rg < 16; ++rg) { const int k0 = crow(rg, hi), k1 = k0 + 32;
;             p0[rg] = (k0 >= lo && k0 <= hv) ? p0[rg] : NEGB; p1[rg] = (k1 >= lo && k1 <= hv) ? p1[rg] : NEGB; }
;     }
; DI void nsa_unit(const Ctx& c0, int b, int g, int i, LAS unsigned char* lds) {
;     ...
;             const bool more = rem != 0ull; int nn = 0;
;             if (more) { nn = __builtin_ctzll(rem); rem &= rem - 1ull; tr = tile_fetch(Kg, Vg, 64 * nn, tid); }
;             const bool selb = (mysel >> n) & 1ull;
;             const int lo = selb ? 0 : 64; const int hv = (n == i) ? ql : 63;
;             tile_compute<false>(lds, k & 1, qr, lo, hv, st, dum0, dum1, 0, wsf, lane);
.LBB0_570:
	s_or_b64 exec, exec, s[14:15]
	v_lshrrev_b64 v[4:5], s100, v[116:117]
	v_add_u32_e32 v5, s84, v137
	v_add_u32_e32 v6, v5, v139
	s_cmp_eq_u32 s25, s100
	s_cselect_b64 s[80:81], -1, 0
	ds_read_b128 v[66:69], v6
	ds_read_b128 v[50:53], v6 offset:512
	v_add_u32_e32 v6, v5, v143
	v_and_b32_e32 v2, 1, v4
	ds_read_b128 v[12:15], v6 offset:2048
	ds_read_b128 v[108:111], v6 offset:2560
	v_add_u32_e32 v6, v5, v146
	v_add_u32_e32 v5, v5, v147
	ds_read_b128 v[112:115], v6 offset:4096
	ds_read_b128 v[120:123], v6 offset:4608
	v_cmp_eq_u64_e32 vcc, 0, v[2:3]
	v_cndmask_b32_e64 v4, 63, v125, s[80:81]
	v_cmp_ne_u32_e64 s[82:83], 63, v4
	v_cndmask_b32_e64 v2, 0, 64, vcc
	s_waitcnt lgkmcnt(5)
	v_mfma_f32_32x32x16_bf16 v[66:81], v[66:69], v[82:85], 0
	v_cmp_gt_u32_e64 s[80:81], v2, v4
	s_or_b64 s[14:15], s[82:83], vcc
	s_xor_b64 vcc, s[14:15], s[80:81]
	s_waitcnt lgkmcnt(4)
	v_mfma_f32_32x32x16_bf16 v[50:65], v[50:53], v[82:85], 0
	s_waitcnt lgkmcnt(3)
	v_mfma_f32_32x32x16_bf16 v[66:81], v[12:15], v[90:93], v[66:81]
	ds_read_b128 v[12:15], v5 offset:6144
	s_waitcnt lgkmcnt(3)
	v_mfma_f32_32x32x16_bf16 v[50:65], v[108:111], v[90:93], v[50:65]
	ds_read_b128 v[108:111], v5 offset:6656
	s_and_b64 s[82:83], vcc, exec
	s_cmp_eq_u64 s[82:83], 0
	s_cselect_b64 s[14:15], -1, 0
	s_waitcnt lgkmcnt(3)
	v_mfma_f32_32x32x16_bf16 v[66:81], v[112:115], v[86:89], v[66:81]
	s_waitcnt lgkmcnt(2)
	v_mfma_f32_32x32x16_bf16 v[50:65], v[120:123], v[86:89], v[50:65]
	s_waitcnt lgkmcnt(1)
	v_mfma_f32_32x32x16_bf16 v[66:81], v[12:15], v[94:97], v[66:81]
	s_waitcnt lgkmcnt(0)
	v_mfma_f32_32x32x16_bf16 v[50:65], v[108:111], v[94:97], v[50:65]
	s_cbranch_vccz .LBB0_572
	v_sub_u32_e32 v249, v4, v148
	v_sub_u32_e32 v249, v249, v2
	v_cmp_gt_i32_e32 vcc, 0, v249
	v_cmp_gt_i32_e64 s[82:83], 32, v249
	s_nop 7
	v_cndmask_b32_e32 v66, v66, v222, vcc
	v_cmp_gt_i32_e32 vcc, 1, v249
	v_cndmask_b32_e64 v50, v50, v222, s[82:83]
	v_cmp_gt_i32_e64 s[82:83], 33, v249
	v_cndmask_b32_e32 v67, v67, v222, vcc
	v_cmp_gt_i32_e32 vcc, 2, v249
	v_cndmask_b32_e64 v51, v51, v222, s[82:83]
	v_cmp_gt_i32_e64 s[82:83], 34, v249
	v_cndmask_b32_e32 v68, v68, v222, vcc
	v_cmp_gt_i32_e32 vcc, 3, v249
	v_cndmask_b32_e64 v52, v52, v222, s[82:83]
	v_cmp_gt_i32_e64 s[82:83], 35, v249
	v_cndmask_b32_e32 v69, v69, v222, vcc
	v_cmp_gt_i32_e32 vcc, 8, v249
	v_cndmask_b32_e64 v53, v53, v222, s[82:83]
	v_cmp_gt_i32_e64 s[82:83], 40, v249
	v_cndmask_b32_e32 v70, v70, v222, vcc
	v_cmp_gt_i32_e32 vcc, 9, v249
	v_cndmask_b32_e64 v54, v54, v222, s[82:83]
	v_cmp_gt_i32_e64 s[82:83], 41, v249
	v_cndmask_b32_e32 v71, v71, v222, vcc
	v_cmp_gt_i32_e32 vcc, 10, v249
	v_cndmask_b32_e64 v55, v55, v222, s[82:83]
	v_cmp_gt_i32_e64 s[82:83], 42, v249
	v_cndmask_b32_e32 v72, v72, v222, vcc
	v_cmp_gt_i32_e32 vcc, 11, v249
	v_cndmask_b32_e64 v56, v56, v222, s[82:83]
	v_cmp_gt_i32_e64 s[82:83], 43, v249
	v_cndmask_b32_e32 v73, v73, v222, vcc
	v_cmp_gt_i32_e32 vcc, 16, v249
	v_cndmask_b32_e64 v57, v57, v222, s[82:83]
	v_cmp_gt_i32_e64 s[82:83], 48, v249
	v_cndmask_b32_e32 v74, v74, v222, vcc
	v_cmp_gt_i32_e32 vcc, 17, v249
	v_cndmask_b32_e64 v58, v58, v222, s[82:83]
	v_cmp_gt_i32_e64 s[82:83], 49, v249
	v_cndmask_b32_e32 v75, v75, v222, vcc
	v_cmp_gt_i32_e32 vcc, 18, v249
	v_cndmask_b32_e64 v59, v59, v222, s[82:83]
	v_cmp_gt_i32_e64 s[82:83], 50, v249
	v_cndmask_b32_e32 v76, v76, v222, vcc
	v_cmp_gt_i32_e32 vcc, 19, v249
	v_cndmask_b32_e64 v60, v60, v222, s[82:83]
	v_cmp_gt_i32_e64 s[82:83], 51, v249
	v_cndmask_b32_e32 v77, v77, v222, vcc
	v_cmp_gt_i32_e32 vcc, 24, v249
	v_cndmask_b32_e64 v61, v61, v222, s[82:83]
	v_cmp_gt_i32_e64 s[82:83], 56, v249
	v_cndmask_b32_e32 v78, v78, v222, vcc
	v_cmp_gt_i32_e32 vcc, 25, v249
	v_cndmask_b32_e64 v62, v62, v222, s[82:83]
	v_cmp_gt_i32_e64 s[82:83], 57, v249
	v_cndmask_b32_e32 v79, v79, v222, vcc
	v_cmp_gt_i32_e32 vcc, 26, v249
	v_cndmask_b32_e64 v63, v63, v222, s[82:83]
	v_cmp_gt_i32_e64 s[82:83], 58, v249
	v_cndmask_b32_e32 v80, v80, v222, vcc
	v_cmp_gt_i32_e32 vcc, 27, v249
	v_cndmask_b32_e64 v64, v64, v222, s[82:83]
	v_cmp_gt_i32_e64 s[82:83], 59, v249
	v_cndmask_b32_e32 v81, v81, v222, vcc
	s_nop 0
	v_cndmask_b32_e64 v65, v65, v222, s[82:83]

; DI int crow(int reg, int hi) { return (reg & 3) + 8 * (reg >> 2) + 4 * hi; }
; template <bool CMP> DI void tile_compute(LAS unsigned char* lds, int buf, const bf16x8 (&q)[4], int lo, int hv, ASt& st, f32x16& imp0, f32x16& imp1, int jt, LAS float* wsf, int lane) {
;     ...
;     const bool dead = lo > hv;
;     const bool part = !dead && (lo > 0 || hv < 63);
;     const bool anyPart = __builtin_amdgcn_ballot_w64(part) != 0ull;
;     if (anyPart) {
; #pragma unroll
;         for (int rg = 0; rg < 16; ++rg) { const int k0 = crow(rg, hi), k1 = k0 + 32;
;             p0[rg] = (k0 >= lo && k0 <= hv) ? p0[rg] : NEGB; p1[rg] = (k1 >= lo && k1 <= hv) ? p1[rg] : NEGB; }
;     }
; DI void nsa_unit(const Ctx& c0, int b, int g, int i, LAS unsigned char* lds) {
;     ...
;             if (n - 1 >= nlast) tr = tile_fetch(Kg, Vg, 64 * (n - 1), tid);
;             int lo = 0, hv = 63;
;             if (n == i) hv = ql;
;             if (n == i - 8) lo = ql + 1;
;             tile_compute<false>(lds, k & 1, qr, lo, hv, st, dum0, dum1, 0, wsf, lane);
.LBB0_590:
	v_add_u32_e32 v79, s88, v137
	v_add_u32_e32 v52, v79, v139
	ds_read_b128 v[36:39], v52
	v_add_u32_e32 v80, v79, v143
	ds_read_b128 v[52:55], v52 offset:512
	ds_read_b128 v[98:101], v80 offset:2048
	ds_read_b128 v[102:105], v80 offset:2560
	v_add_u32_e32 v80, v79, v146
	v_add_u32_e32 v79, v79, v147
	ds_read_b128 v[106:109], v80 offset:4096
	ds_read_b128 v[110:113], v80 offset:4608
	s_cmp_eq_u32 s12, 0xffff2000
	s_cselect_b64 vcc, -1, 0
	s_waitcnt lgkmcnt(5)
	v_mfma_f32_32x32x16_bf16 v[36:51], v[36:39], v[82:85], 0
	s_waitcnt lgkmcnt(4)
	v_mfma_f32_32x32x16_bf16 v[52:67], v[52:55], v[82:85], 0
	s_waitcnt lgkmcnt(3)
	v_mfma_f32_32x32x16_bf16 v[36:51], v[98:101], v[90:93], v[36:51]
	ds_read_b128 v[98:101], v79 offset:6144
	s_waitcnt lgkmcnt(3)
	v_mfma_f32_32x32x16_bf16 v[52:67], v[102:105], v[90:93], v[52:67]
	ds_read_b128 v[102:105], v79 offset:6656
	v_cndmask_b32_e32 v79, 0, v210, vcc
	v_cmp_lt_u32_e64 s[78:79], 63, v79
	s_xor_b64 vcc, vcc, s[78:79]
	s_and_b64 s[80:81], vcc, exec
	s_cmp_eq_u64 s[80:81], 0
	s_waitcnt lgkmcnt(3)
	v_mfma_f32_32x32x16_bf16 v[36:51], v[106:109], v[86:89], v[36:51]
	s_waitcnt lgkmcnt(2)
	v_mfma_f32_32x32x16_bf16 v[52:67], v[110:113], v[86:89], v[52:67]
	s_waitcnt lgkmcnt(1)
	v_mfma_f32_32x32x16_bf16 v[36:51], v[98:101], v[94:97], v[36:51]
	s_cselect_b64 s[14:15], -1, 0
	s_waitcnt lgkmcnt(0)
	v_mfma_f32_32x32x16_bf16 v[52:67], v[102:105], v[94:97], v[52:67]
	s_cbranch_vccz .LBB0_592
	v_cmp_ge_u32_e32 vcc, v148, v79
	s_nop 7
	v_cndmask_b32_e32 v36, v222, v36, vcc
	v_cmp_ge_u32_e32 vcc, v149, v79
	s_nop 1
	v_cndmask_b32_e32 v52, v222, v52, vcc
	v_cmp_ge_u32_e32 vcc, v154, v79
	s_nop 1
	v_cndmask_b32_e32 v37, v222, v37, vcc
	v_cmp_ge_u32_e32 vcc, v155, v79
	s_nop 1
	v_cndmask_b32_e32 v53, v222, v53, vcc
	v_cmp_ge_u32_e32 vcc, v156, v79
	s_nop 1
	v_cndmask_b32_e32 v38, v222, v38, vcc
	v_cmp_ge_u32_e32 vcc, v157, v79
	s_nop 1
	v_cndmask_b32_e32 v54, v222, v54, vcc
	v_cmp_ge_u32_e32 vcc, v158, v79
	s_nop 1
	v_cndmask_b32_e32 v39, v222, v39, vcc
	v_cmp_ge_u32_e32 vcc, v159, v79
	s_nop 1
	v_cndmask_b32_e32 v55, v222, v55, vcc
	v_cmp_ge_u32_e32 vcc, v160, v79
	s_nop 1
	v_cndmask_b32_e32 v40, v222, v40, vcc
	v_cmp_ge_u32_e32 vcc, v161, v79
	s_nop 1
	v_cndmask_b32_e32 v56, v222, v56, vcc
	v_cmp_ge_u32_e32 vcc, v162, v79
	s_nop 1
	v_cndmask_b32_e32 v41, v222, v41, vcc
	v_cmp_ge_u32_e32 vcc, v163, v79
	s_nop 1
	v_cndmask_b32_e32 v57, v222, v57, vcc
	v_cmp_ge_u32_e32 vcc, v164, v79
	s_nop 1
	v_cndmask_b32_e32 v42, v222, v42, vcc
	v_cmp_ge_u32_e32 vcc, v165, v79
	s_nop 1
	v_cndmask_b32_e32 v58, v222, v58, vcc
	v_cmp_ge_u32_e32 vcc, v166, v79
	s_nop 1
	v_cndmask_b32_e32 v43, v222, v43, vcc
	v_cmp_ge_u32_e32 vcc, v167, v79
	s_nop 1
	v_cndmask_b32_e32 v59, v222, v59, vcc
	v_cmp_ge_u32_e32 vcc, v168, v79
	s_nop 1
	v_cndmask_b32_e32 v44, v222, v44, vcc
	v_cmp_ge_u32_e32 vcc, v169, v79
	s_nop 1
	v_cndmask_b32_e32 v60, v222, v60, vcc
	v_cmp_ge_u32_e32 vcc, v170, v79
	s_nop 1
	v_cndmask_b32_e32 v45, v222, v45, vcc
	v_cmp_ge_u32_e32 vcc, v171, v79
	s_nop 1
	v_cndmask_b32_e32 v61, v222, v61, vcc
	v_cmp_ge_u32_e32 vcc, v172, v79
	s_nop 1
	v_cndmask_b32_e32 v46, v222, v46, vcc
	v_cmp_ge_u32_e32 vcc, v173, v79
	s_nop 1
	v_cndmask_b32_e32 v62, v222, v62, vcc
	v_cmp_ge_u32_e32 vcc, v174, v79
	s_nop 1
	v_cndmask_b32_e32 v47, v222, v47, vcc
	v_cmp_ge_u32_e32 vcc, v175, v79
	s_nop 1
	v_cndmask_b32_e32 v63, v222, v63, vcc
	v_cmp_ge_u32_e32 vcc, v176, v79
	s_nop 1
	v_cndmask_b32_e32 v48, v222, v48, vcc
	v_cmp_ge_u32_e32 vcc, v177, v79
	s_nop 1
	v_cndmask_b32_e32 v64, v222, v64, vcc
	v_cmp_ge_u32_e32 vcc, v178, v79
	s_nop 1
	v_cndmask_b32_e32 v49, v222, v49, vcc
	v_cmp_ge_u32_e32 vcc, v179, v79
	s_nop 1
	v_cndmask_b32_e32 v65, v222, v65, vcc
	v_cmp_ge_u32_e32 vcc, v180, v79
	s_nop 1
	v_cndmask_b32_e32 v50, v222, v50, vcc
	v_cmp_ge_u32_e32 vcc, v181, v79
	s_nop 1
	v_cndmask_b32_e32 v66, v222, v66, vcc
	v_cmp_ge_u32_e32 vcc, v182, v79
	s_nop 1
	v_cndmask_b32_e32 v51, v222, v51, vcc
	v_cmp_ge_u32_e32 vcc, v183, v79
	s_nop 1
	v_cndmask_b32_e32 v67, v222, v67, vcc

; #define LAS __attribute__((address_space(3)))
; DI int crow(int reg, int hi) { return (reg & 3) + 8 * (reg >> 2) + 4 * hi; }
; #define MFMA32(a, b, c) __builtin_amdgcn_mfma_f32_32x32x16_bf16((a), (b), (c), 0, 0, 0)
; template <bool CMP> DI void tile_compute(LAS unsigned char* lds, int buf, const bf16x8 (&q)[4], int lo, int hv, ASt& st, f32x16& imp0, f32x16& imp1, int jt, LAS float* wsf, int lane) {
;     const int r = lane & 31, hi = lane >> 5;
;     const LAS unsigned char* kb0 = lds + A_KT + buf * 8192 + hi * 1024;
;     f32x16 p0 = {}, p1 = {};
; #pragma unroll
;     for (int s = 0; s < 4; ++s) { const LAS unsigned char* kb = kb0 + ((r ^ (4 * s + 2 * hi)) * 16);
;         const bf16x8 a0 = *(const LAS bf16x8*)(kb + s * 2048), a1 = *(const LAS bf16x8*)(kb + s * 2048 + 512);
;         p0 = MFMA32(a0, q[s], p0); p1 = MFMA32(a1, q[s], p1); }
;     const bool dead = lo > hv;
;     const bool part = !dead && (lo > 0 || hv < 63);
;     const bool anyPart = __builtin_amdgcn_ballot_w64(part) != 0ull;
;     if (anyPart) {
; #pragma unroll
;         for (int rg = 0; rg < 16; ++rg) { const int k0 = crow(rg, hi), k1 = k0 + 32;
;             p0[rg] = (k0 >= lo && k0 <= hv) ? p0[rg] : NEGB; p1[rg] = (k1 >= lo && k1 <= hv) ? p1[rg] : NEGB; }
;     }
; DI void nsa_unit(const Ctx& c0, int b, int g, int i, LAS unsigned char* lds) {
;     ...
;             int hv = jmax - 64 * k; hv = hv > 63 ? 63 : hv; const int lo = hv < 0 ? 64 : 0;
.LBB0_1162:
	v_add_u32_e32 v229, s28, v137
	v_add_u32_e32 v72, v229, v139
	ds_read_b128 v[68:71], v72
	ds_read_b128 v[72:75], v72 offset:512
	v_add_u32_e32 v141, v229, v143
	ds_read_b128 v[230:233], v141 offset:2048
	ds_read_b128 v[234:237], v141 offset:2560
	v_add_u32_e32 v141, v229, v146
	s_waitcnt lgkmcnt(0)
	v_mfma_f32_32x32x16_bf16 v[84:99], v[68:71], v[112:115], 0
	v_add_u32_e32 v238, v229, v147
	v_lshrrev_b32_e32 v229, 25, v226
	v_and_b32_e32 v229, 64, v229
	v_cmp_gt_i32_e64 s[86:87], 63, v226
	v_mfma_f32_32x32x16_bf16 v[68:83], v[72:75], v[112:115], 0
	v_mfma_f32_32x32x16_bf16 v[84:99], v[230:233], v[100:103], v[84:99]
	v_mfma_f32_32x32x16_bf16 v[68:83], v[234:237], v[100:103], v[68:83]
	ds_read_b128 v[230:233], v141 offset:4096
	ds_read_b128 v[234:237], v141 offset:4608
	v_min_i32_e32 v141, 63, v226
	v_cmp_le_i32_e32 vcc, v229, v141
	v_cmp_gt_i32_e64 s[80:81], v229, v141
	s_waitcnt lgkmcnt(0)
	v_mfma_f32_32x32x16_bf16 v[84:99], v[230:233], v[108:111], v[84:99]
	ds_read_b128 v[230:233], v238 offset:6144
	v_mfma_f32_32x32x16_bf16 v[68:83], v[234:237], v[108:111], v[68:83]
	ds_read_b128 v[234:237], v238 offset:6656
	v_and_b32_e32 v238, 0x80000000, v226
	v_cmp_ne_u32_e64 s[82:83], 0, v238
	s_or_b64 s[14:15], s[86:87], s[82:83]
	s_and_b64 s[14:15], s[14:15], vcc
	s_waitcnt lgkmcnt(0)
	v_mfma_f32_32x32x16_bf16 v[84:99], v[230:233], v[104:107], v[84:99]
	s_and_b64 vcc, s[14:15], exec
	s_cmp_eq_u64 vcc, 0
	s_cselect_b64 s[14:15], -1, 0
	v_mfma_f32_32x32x16_bf16 v[68:83], v[234:237], v[104:107], v[68:83]
	s_cbranch_vccz .LBB0_1164
	v_sub_u32_e32 v249, v141, v148
	v_sub_u32_e32 v249, v249, v229
	v_cmp_gt_i32_e32 vcc, 0, v249
	v_cmp_gt_i32_e64 s[82:83], 32, v249
	s_nop 7
	v_cndmask_b32_e32 v84, v84, v217, vcc
	v_cmp_gt_i32_e32 vcc, 1, v249
	v_cndmask_b32_e64 v68, v68, v217, s[82:83]
	v_cmp_gt_i32_e64 s[82:83], 33, v249
	v_cndmask_b32_e32 v85, v85, v217, vcc
	v_cmp_gt_i32_e32 vcc, 2, v249
	v_cndmask_b32_e64 v69, v69, v217, s[82:83]
	v_cmp_gt_i32_e64 s[82:83], 34, v249
	v_cndmask_b32_e32 v86, v86, v217, vcc
	v_cmp_gt_i32_e32 vcc, 3, v249
	v_cndmask_b32_e64 v70, v70, v217, s[82:83]
	v_cmp_gt_i32_e64 s[82:83], 35, v249
	v_cndmask_b32_e32 v87, v87, v217, vcc
	v_cmp_gt_i32_e32 vcc, 8, v249
	v_cndmask_b32_e64 v71, v71, v217, s[82:83]
	v_cmp_gt_i32_e64 s[82:83], 40, v249
	v_cndmask_b32_e32 v88, v88, v217, vcc
	v_cmp_gt_i32_e32 vcc, 9, v249
	v_cndmask_b32_e64 v72, v72, v217, s[82:83]
	v_cmp_gt_i32_e64 s[82:83], 41, v249
	v_cndmask_b32_e32 v89, v89, v217, vcc
	v_cmp_gt_i32_e32 vcc, 10, v249
	v_cndmask_b32_e64 v73, v73, v217, s[82:83]
	v_cmp_gt_i32_e64 s[82:83], 42, v249
	v_cndmask_b32_e32 v90, v90, v217, vcc
	v_cmp_gt_i32_e32 vcc, 11, v249
	v_cndmask_b32_e64 v74, v74, v217, s[82:83]
	v_cmp_gt_i32_e64 s[82:83], 43, v249
	v_cndmask_b32_e32 v91, v91, v217, vcc
	v_cmp_gt_i32_e32 vcc, 16, v249
	v_cndmask_b32_e64 v75, v75, v217, s[82:83]
	v_cmp_gt_i32_e64 s[82:83], 48, v249
	v_cndmask_b32_e32 v92, v92, v217, vcc
	v_cmp_gt_i32_e32 vcc, 17, v249
	v_cndmask_b32_e64 v76, v76, v217, s[82:83]
	v_cmp_gt_i32_e64 s[82:83], 49, v249
	v_cndmask_b32_e32 v93, v93, v217, vcc
	v_cmp_gt_i32_e32 vcc, 18, v249
	v_cndmask_b32_e64 v77, v77, v217, s[82:83]
	v_cmp_gt_i32_e64 s[82:83], 50, v249
	v_cndmask_b32_e32 v94, v94, v217, vcc
	v_cmp_gt_i32_e32 vcc, 19, v249
	v_cndmask_b32_e64 v78, v78, v217, s[82:83]
	v_cmp_gt_i32_e64 s[82:83], 51, v249
	v_cndmask_b32_e32 v95, v95, v217, vcc
	v_cmp_gt_i32_e32 vcc, 24, v249
	v_cndmask_b32_e64 v79, v79, v217, s[82:83]
	v_cmp_gt_i32_e64 s[82:83], 56, v249
	v_cndmask_b32_e32 v96, v96, v217, vcc
	v_cmp_gt_i32_e32 vcc, 25, v249
	v_cndmask_b32_e64 v80, v80, v217, s[82:83]
	v_cmp_gt_i32_e64 s[82:83], 57, v249
	v_cndmask_b32_e32 v97, v97, v217, vcc
	v_cmp_gt_i32_e32 vcc, 26, v249
	v_cndmask_b32_e64 v81, v81, v217, s[82:83]
	v_cmp_gt_i32_e64 s[82:83], 58, v249
	v_cndmask_b32_e32 v98, v98, v217, vcc
	v_cmp_gt_i32_e32 vcc, 27, v249
	v_cndmask_b32_e64 v82, v82, v217, s[82:83]
	v_cmp_gt_i32_e64 s[82:83], 59, v249
	v_cndmask_b32_e32 v99, v99, v217, vcc
	s_nop 0
	v_cndmask_b32_e64 v83, v83, v217, s[82:83]

; #define LAS __attribute__((address_space(3)))
; DI int crow(int reg, int hi) { return (reg & 3) + 8 * (reg >> 2) + 4 * hi; }
; #define MFMA32(a, b, c) __builtin_amdgcn_mfma_f32_32x32x16_bf16((a), (b), (c), 0, 0, 0)
; template <bool CMP> DI void tile_compute(LAS unsigned char* lds, int buf, const bf16x8 (&q)[4], int lo, int hv, ASt& st, f32x16& imp0, f32x16& imp1, int jt, LAS float* wsf, int lane) {
;     const int r = lane & 31, hi = lane >> 5;
;     const LAS unsigned char* kb0 = lds + A_KT + buf * 8192 + hi * 1024;
;     f32x16 p0 = {}, p1 = {};
; #pragma unroll
;     for (int s = 0; s < 4; ++s) { const LAS unsigned char* kb = kb0 + ((r ^ (4 * s + 2 * hi)) * 16);
;         const bf16x8 a0 = *(const LAS bf16x8*)(kb + s * 2048), a1 = *(const LAS bf16x8*)(kb + s * 2048 + 512);
;         p0 = MFMA32(a0, q[s], p0); p1 = MFMA32(a1, q[s], p1); }
;     const bool dead = lo > hv;
;     const bool part = !dead && (lo > 0 || hv < 63);
;     const bool anyPart = __builtin_amdgcn_ballot_w64(part) != 0ull;
;     if (anyPart) {
; #pragma unroll
;         for (int rg = 0; rg < 16; ++rg) { const int k0 = crow(rg, hi), k1 = k0 + 32;
;             p0[rg] = (k0 >= lo && k0 <= hv) ? p0[rg] : NEGB; p1[rg] = (k1 >= lo && k1 <= hv) ? p1[rg] : NEGB; }
;     }
; DI void nsa_unit(const Ctx& c0, int b, int g, int i, LAS unsigned char* lds) {
;     ...
;             const bool more = rem != 0ull; int nn = 0;
;             if (more) { nn = __builtin_ctzll(rem); rem &= rem - 1ull; tr = tile_fetch(Kg, Vg, 64 * nn, tid); }
;             const bool selb = (mysel >> n) & 1ull;
;             const int lo = selb ? 0 : 64; const int hv = (n == i) ? ql : 63;
;             tile_compute<false>(lds, k & 1, qr, lo, hv, st, dum0, dum1, 0, wsf, lane);
.LBB0_1183:
	s_or_b64 exec, exec, s[16:17]
	v_lshrrev_b64 v[4:5], s100, v[116:117]
	v_add_u32_e32 v5, s28, v137
	v_add_u32_e32 v6, v5, v139
	s_cmp_eq_u32 s27, s100
	s_cselect_b64 s[82:83], -1, 0
	ds_read_b128 v[66:69], v6
	ds_read_b128 v[50:53], v6 offset:512
	v_add_u32_e32 v6, v5, v143
	v_and_b32_e32 v2, 1, v4
	ds_read_b128 v[12:15], v6 offset:2048
	ds_read_b128 v[108:111], v6 offset:2560
	v_add_u32_e32 v6, v5, v146
	v_add_u32_e32 v5, v5, v147
	ds_read_b128 v[112:115], v6 offset:4096
	ds_read_b128 v[120:123], v6 offset:4608
	v_cmp_eq_u64_e32 vcc, 0, v[2:3]
	v_cndmask_b32_e64 v4, 63, v125, s[82:83]
	v_cmp_ne_u32_e64 s[86:87], 63, v4
	v_cndmask_b32_e64 v2, 0, 64, vcc
	s_waitcnt lgkmcnt(5)
	v_mfma_f32_32x32x16_bf16 v[66:81], v[66:69], v[82:85], 0
	v_cmp_gt_u32_e64 s[82:83], v2, v4
	s_or_b64 s[16:17], s[86:87], vcc
	s_xor_b64 vcc, s[16:17], s[82:83]
	s_waitcnt lgkmcnt(4)
	v_mfma_f32_32x32x16_bf16 v[50:65], v[50:53], v[82:85], 0
	s_waitcnt lgkmcnt(3)
	v_mfma_f32_32x32x16_bf16 v[66:81], v[12:15], v[90:93], v[66:81]
	ds_read_b128 v[12:15], v5 offset:6144
	s_waitcnt lgkmcnt(3)
	v_mfma_f32_32x32x16_bf16 v[50:65], v[108:111], v[90:93], v[50:65]
	ds_read_b128 v[108:111], v5 offset:6656
	s_and_b64 s[86:87], vcc, exec
	s_cmp_eq_u64 s[86:87], 0
	s_cselect_b64 s[16:17], -1, 0
	s_waitcnt lgkmcnt(3)
	v_mfma_f32_32x32x16_bf16 v[66:81], v[112:115], v[86:89], v[66:81]
	s_waitcnt lgkmcnt(2)
	v_mfma_f32_32x32x16_bf16 v[50:65], v[120:123], v[86:89], v[50:65]
	s_waitcnt lgkmcnt(1)
	v_mfma_f32_32x32x16_bf16 v[66:81], v[12:15], v[94:97], v[66:81]
	s_waitcnt lgkmcnt(0)
	v_mfma_f32_32x32x16_bf16 v[50:65], v[108:111], v[94:97], v[50:65]
	s_cbranch_vccz .LBB0_1185
	v_sub_u32_e32 v249, v4, v148
	v_sub_u32_e32 v249, v249, v2
	v_cmp_gt_i32_e32 vcc, 0, v249
	v_cmp_gt_i32_e64 s[86:87], 32, v249
	s_nop 7
	v_cndmask_b32_e32 v66, v66, v217, vcc
	v_cmp_gt_i32_e32 vcc, 1, v249
	v_cndmask_b32_e64 v50, v50, v217, s[86:87]
	v_cmp_gt_i32_e64 s[86:87], 33, v249
	v_cndmask_b32_e32 v67, v67, v217, vcc
	v_cmp_gt_i32_e32 vcc, 2, v249
	v_cndmask_b32_e64 v51, v51, v217, s[86:87]
	v_cmp_gt_i32_e64 s[86:87], 34, v249
	v_cndmask_b32_e32 v68, v68, v217, vcc
	v_cmp_gt_i32_e32 vcc, 3, v249
	v_cndmask_b32_e64 v52, v52, v217, s[86:87]
	v_cmp_gt_i32_e64 s[86:87], 35, v249
	v_cndmask_b32_e32 v69, v69, v217, vcc
	v_cmp_gt_i32_e32 vcc, 8, v249
	v_cndmask_b32_e64 v53, v53, v217, s[86:87]
	v_cmp_gt_i32_e64 s[86:87], 40, v249
	v_cndmask_b32_e32 v70, v70, v217, vcc
	v_cmp_gt_i32_e32 vcc, 9, v249
	v_cndmask_b32_e64 v54, v54, v217, s[86:87]
	v_cmp_gt_i32_e64 s[86:87], 41, v249
	v_cndmask_b32_e32 v71, v71, v217, vcc
	v_cmp_gt_i32_e32 vcc, 10, v249
	v_cndmask_b32_e64 v55, v55, v217, s[86:87]
	v_cmp_gt_i32_e64 s[86:87], 42, v249
	v_cndmask_b32_e32 v72, v72, v217, vcc
	v_cmp_gt_i32_e32 vcc, 11, v249
	v_cndmask_b32_e64 v56, v56, v217, s[86:87]
	v_cmp_gt_i32_e64 s[86:87], 43, v249
	v_cndmask_b32_e32 v73, v73, v217, vcc
	v_cmp_gt_i32_e32 vcc, 16, v249
	v_cndmask_b32_e64 v57, v57, v217, s[86:87]
	v_cmp_gt_i32_e64 s[86:87], 48, v249
	v_cndmask_b32_e32 v74, v74, v217, vcc
	v_cmp_gt_i32_e32 vcc, 17, v249
	v_cndmask_b32_e64 v58, v58, v217, s[86:87]
	v_cmp_gt_i32_e64 s[86:87], 49, v249
	v_cndmask_b32_e32 v75, v75, v217, vcc
	v_cmp_gt_i32_e32 vcc, 18, v249
	v_cndmask_b32_e64 v59, v59, v217, s[86:87]
	v_cmp_gt_i32_e64 s[86:87], 50, v249
	v_cndmask_b32_e32 v76, v76, v217, vcc
	v_cmp_gt_i32_e32 vcc, 19, v249
	v_cndmask_b32_e64 v60, v60, v217, s[86:87]
	v_cmp_gt_i32_e64 s[86:87], 51, v249
	v_cndmask_b32_e32 v77, v77, v217, vcc
	v_cmp_gt_i32_e32 vcc, 24, v249
	v_cndmask_b32_e64 v61, v61, v217, s[86:87]
	v_cmp_gt_i32_e64 s[86:87], 56, v249
	v_cndmask_b32_e32 v78, v78, v217, vcc
	v_cmp_gt_i32_e32 vcc, 25, v249
	v_cndmask_b32_e64 v62, v62, v217, s[86:87]
	v_cmp_gt_i32_e64 s[86:87], 57, v249
	v_cndmask_b32_e32 v79, v79, v217, vcc
	v_cmp_gt_i32_e32 vcc, 26, v249
	v_cndmask_b32_e64 v63, v63, v217, s[86:87]
	v_cmp_gt_i32_e64 s[86:87], 58, v249
	v_cndmask_b32_e32 v80, v80, v217, vcc
	v_cmp_gt_i32_e32 vcc, 27, v249
	v_cndmask_b32_e64 v64, v64, v217, s[86:87]
	v_cmp_gt_i32_e64 s[86:87], 59, v249
	v_cndmask_b32_e32 v81, v81, v217, vcc
	s_nop 0
	v_cndmask_b32_e64 v65, v65, v217, s[86:87]

; DI int crow(int reg, int hi) { return (reg & 3) + 8 * (reg >> 2) + 4 * hi; }
; template <bool CMP> DI void tile_compute(LAS unsigned char* lds, int buf, const bf16x8 (&q)[4], int lo, int hv, ASt& st, f32x16& imp0, f32x16& imp1, int jt, LAS float* wsf, int lane) {
;     ...
;     const bool dead = lo > hv;
;     const bool part = !dead && (lo > 0 || hv < 63);
;     const bool anyPart = __builtin_amdgcn_ballot_w64(part) != 0ull;
;     if (anyPart) {
; #pragma unroll
;         for (int rg = 0; rg < 16; ++rg) { const int k0 = crow(rg, hi), k1 = k0 + 32;
;             p0[rg] = (k0 >= lo && k0 <= hv) ? p0[rg] : NEGB; p1[rg] = (k1 >= lo && k1 <= hv) ? p1[rg] : NEGB; }
;     }
; DI void nsa_unit(const Ctx& c0, int b, int g, int i, LAS unsigned char* lds) {
;     ...
;             if (n - 1 >= nlast) tr = tile_fetch(Kg, Vg, 64 * (n - 1), tid);
;             int lo = 0, hv = 63;
;             if (n == i) hv = ql;
;             if (n == i - 8) lo = ql + 1;
;             tile_compute<false>(lds, k & 1, qr, lo, hv, st, dum0, dum1, 0, wsf, lane);
.LBB0_1203:
	v_add_u32_e32 v79, s28, v137
	v_add_u32_e32 v52, v79, v139
	ds_read_b128 v[36:39], v52
	v_add_u32_e32 v80, v79, v143
	ds_read_b128 v[52:55], v52 offset:512
	ds_read_b128 v[98:101], v80 offset:2048
	ds_read_b128 v[102:105], v80 offset:2560
	v_add_u32_e32 v80, v79, v146
	v_add_u32_e32 v79, v79, v147
	ds_read_b128 v[106:109], v80 offset:4096
	ds_read_b128 v[110:113], v80 offset:4608
	s_cmp_eq_u32 s14, 0xffff2000
	s_cselect_b64 vcc, -1, 0
	s_waitcnt lgkmcnt(5)
	v_mfma_f32_32x32x16_bf16 v[36:51], v[36:39], v[82:85], 0
	s_waitcnt lgkmcnt(4)
	v_mfma_f32_32x32x16_bf16 v[52:67], v[52:55], v[82:85], 0
	s_waitcnt lgkmcnt(3)
	v_mfma_f32_32x32x16_bf16 v[36:51], v[98:101], v[90:93], v[36:51]
	ds_read_b128 v[98:101], v79 offset:6144
	s_waitcnt lgkmcnt(3)
	v_mfma_f32_32x32x16_bf16 v[52:67], v[102:105], v[90:93], v[52:67]
	ds_read_b128 v[102:105], v79 offset:6656
	v_cndmask_b32_e32 v79, 0, v208, vcc
	v_cmp_lt_u32_e64 s[80:81], 63, v79
	s_xor_b64 vcc, vcc, s[80:81]
	s_and_b64 s[82:83], vcc, exec
	s_cmp_eq_u64 s[82:83], 0
	s_waitcnt lgkmcnt(3)
	v_mfma_f32_32x32x16_bf16 v[36:51], v[106:109], v[86:89], v[36:51]
	s_waitcnt lgkmcnt(2)
	v_mfma_f32_32x32x16_bf16 v[52:67], v[110:113], v[86:89], v[52:67]
	s_waitcnt lgkmcnt(1)
	v_mfma_f32_32x32x16_bf16 v[36:51], v[98:101], v[94:97], v[36:51]
	s_cselect_b64 s[16:17], -1, 0
	s_waitcnt lgkmcnt(0)
	v_mfma_f32_32x32x16_bf16 v[52:67], v[102:105], v[94:97], v[52:67]
	s_cbranch_vccz .LBB0_1205
	v_cmp_ge_u32_e32 vcc, v148, v79
	s_nop 7
	v_cndmask_b32_e32 v36, v217, v36, vcc
	v_cmp_ge_u32_e32 vcc, v149, v79
	s_nop 1
	v_cndmask_b32_e32 v52, v217, v52, vcc
	v_cmp_ge_u32_e32 vcc, v155, v79
	s_nop 1
	v_cndmask_b32_e32 v37, v217, v37, vcc
	v_cmp_ge_u32_e32 vcc, v156, v79
	s_nop 1
	v_cndmask_b32_e32 v53, v217, v53, vcc
	v_cmp_ge_u32_e32 vcc, v157, v79
	s_nop 1
	v_cndmask_b32_e32 v38, v217, v38, vcc
	v_cmp_ge_u32_e32 vcc, v158, v79
	s_nop 1
	v_cndmask_b32_e32 v54, v217, v54, vcc
	v_cmp_ge_u32_e32 vcc, v159, v79
	s_nop 1
	v_cndmask_b32_e32 v39, v217, v39, vcc
	v_cmp_ge_u32_e32 vcc, v160, v79
	s_nop 1
	v_cndmask_b32_e32 v55, v217, v55, vcc
	v_cmp_ge_u32_e32 vcc, v161, v79
	s_nop 1
	v_cndmask_b32_e32 v40, v217, v40, vcc
	v_cmp_ge_u32_e32 vcc, v162, v79
	s_nop 1
	v_cndmask_b32_e32 v56, v217, v56, vcc
	v_cmp_ge_u32_e32 vcc, v163, v79
	s_nop 1
	v_cndmask_b32_e32 v41, v217, v41, vcc
	v_cmp_ge_u32_e32 vcc, v164, v79
	s_nop 1
	v_cndmask_b32_e32 v57, v217, v57, vcc
	v_cmp_ge_u32_e32 vcc, v165, v79
	s_nop 1
	v_cndmask_b32_e32 v42, v217, v42, vcc
	v_cmp_ge_u32_e32 vcc, v166, v79
	s_nop 1
	v_cndmask_b32_e32 v58, v217, v58, vcc
	v_cmp_ge_u32_e32 vcc, v167, v79
	s_nop 1
	v_cndmask_b32_e32 v43, v217, v43, vcc
	v_cmp_ge_u32_e32 vcc, v168, v79
	s_nop 1
	v_cndmask_b32_e32 v59, v217, v59, vcc
	v_cmp_ge_u32_e32 vcc, v169, v79
	s_nop 1
	v_cndmask_b32_e32 v44, v217, v44, vcc
	v_cmp_ge_u32_e32 vcc, v170, v79
	s_nop 1
	v_cndmask_b32_e32 v60, v217, v60, vcc
	v_cmp_ge_u32_e32 vcc, v171, v79
	s_nop 1
	v_cndmask_b32_e32 v45, v217, v45, vcc
	v_cmp_ge_u32_e32 vcc, v172, v79
	s_nop 1
	v_cndmask_b32_e32 v61, v217, v61, vcc
	v_cmp_ge_u32_e32 vcc, v173, v79
	s_nop 1
	v_cndmask_b32_e32 v46, v217, v46, vcc
	v_cmp_ge_u32_e32 vcc, v174, v79
	s_nop 1
	v_cndmask_b32_e32 v62, v217, v62, vcc
	v_cmp_ge_u32_e32 vcc, v175, v79
	s_nop 1
	v_cndmask_b32_e32 v47, v217, v47, vcc
	v_cmp_ge_u32_e32 vcc, v176, v79
	s_nop 1
	v_cndmask_b32_e32 v63, v217, v63, vcc
	v_cmp_ge_u32_e32 vcc, v177, v79
	s_nop 1
	v_cndmask_b32_e32 v48, v217, v48, vcc
	v_cmp_ge_u32_e32 vcc, v178, v79
	s_nop 1
	v_cndmask_b32_e32 v64, v217, v64, vcc
	v_cmp_ge_u32_e32 vcc, v179, v79
	s_nop 1
	v_cndmask_b32_e32 v49, v217, v49, vcc
	v_cmp_ge_u32_e32 vcc, v180, v79
	s_nop 1
	v_cndmask_b32_e32 v65, v217, v65, vcc
	v_cmp_ge_u32_e32 vcc, v181, v79
	s_nop 1
	v_cndmask_b32_e32 v50, v217, v50, vcc
	v_cmp_ge_u32_e32 vcc, v182, v79
	s_nop 1
	v_cndmask_b32_e32 v66, v217, v66, vcc
	v_cmp_ge_u32_e32 vcc, v183, v79
	s_nop 1
	v_cndmask_b32_e32 v51, v217, v51, vcc
	v_cmp_ge_u32_e32 vcc, v195, v79
	s_nop 1
	v_cndmask_b32_e32 v67, v217, v67, vcc
